# P3: also prefetch epilogue groups 0,4 and 5 row-ssq in-loop; epilogue top waits vmcnt(3)
# baseline (speedup 1.0000x reference)
;     __device__ __forceinline__ void operator()(const f32x4 (&acc)[2][2][4][2], const Unit& u, int wr, int wc, int fr, int fq) const {
;     ...
;         for (int g = 0; g < 8; ++g) { if constexpr (HAS_RS2) r2[g] = __hip_atomic_load(rs2 + row0 + (g >> 2) * HALF + (g & 3) * 16, __ATOMIC_RELAXED, __HIP_MEMORY_SCOPE_AGENT); else if constexpr (HAS_NRM) r2[g] = ssq[NRM_OFF + rown + (g >> 2) * HALF + (g & 3) * 16]; else r2[g] = 0.f; }
;         u32x2 raw[8][2][2];
;         if constexpr (BASEB) {
; #pragma unroll
;             for (int g = 0; g < 4; ++g)
; #pragma unroll
;                 for (int bj = 0; bj < 2; ++bj)
; #pragma unroll
;                     for (int n = 0; n < 2; ++n) raw[g][bj][n] = *(const u32x2*)((const bf16_t*)base + (size_t)(row0 + (g >> 2) * HALF + (g & 3) * 16) * 2048 + col0 + bj * HALF + n * 16);
.LBB0_651:
	s_cmp_eq_u32 s46, 24
	s_cbranch_scc0 .Lp3pf_skip
	v_lshl_add_u32 v230, s24, 8, v1
	v_lshl_or_b32 v232, s22, 8, v196
	v_ashrrev_i32_e32 v233, 31, v232
	v_lshlrev_b64 v[232:233], 1, v[232:233]
	v_ashrrev_i32_e32 v231, 31, v230
	v_lshl_add_u64 v[216:217], v[230:231], 2, s[6:7]
	s_mov_b64 s[40:41], 0x20000
	v_lshlrev_b64 v[230:231], 12, v[230:231]
	v_lshl_add_u64 v[216:217], v[216:217], 0, s[40:41]
	v_lshl_add_u64 v[232:233], s[90:91], 0, v[232:233]
	v_lshl_add_u64 v[230:231], v[232:233], 0, v[230:231]
	global_load_dword v131, v[216:217], off
	global_load_dword v133, v[216:217], off offset:64
	global_load_dword v135, v[216:217], off offset:128
	global_load_dword v137, v[216:217], off offset:192
	global_load_dword v243, v[216:217], off offset:512
	s_mov_b64 s[40:41], 0x80000
	v_lshl_add_u64 v[232:233], v[230:231], 0, s[40:41]
	global_load_dwordx2 v[214:215], v[230:231], off offset:32
	global_load_dwordx2 v[218:219], v[230:231], off offset:256
	global_load_dwordx2 v[220:221], v[230:231], off offset:288
	global_load_dwordx2 v[216:217], v[230:231], off
	global_load_dwordx2 v[222:223], v[232:233], off
	global_load_dwordx2 v[224:225], v[232:233], off offset:32
	global_load_dwordx2 v[226:227], v[232:233], off offset:256
	global_load_dwordx2 v[228:229], v[232:233], off offset:288
	s_mov_b64 s[40:41], 0x10000
	v_lshl_add_u64 v[232:233], v[230:231], 0, s[40:41]
	global_load_dwordx2 v[234:235], v[232:233], off
	global_load_dwordx2 v[236:237], v[232:233], off offset:32
	global_load_dwordx2 v[238:239], v[232:233], off offset:256
	global_load_dwordx2 v[240:241], v[232:233], off offset:288
	s_mov_b64 s[40:41], 0x20000
	v_lshl_add_u64 v[232:233], v[230:231], 0, s[40:41]
	global_load_dwordx2 v[244:245], v[232:233], off
	global_load_dwordx2 v[246:247], v[232:233], off offset:32
	global_load_dwordx2 v[248:249], v[232:233], off offset:256
	global_load_dwordx2 v[250:251], v[232:233], off offset:288
	s_mov_b64 s[40:41], 0x30000
	v_lshl_add_u64 v[232:233], v[230:231], 0, s[40:41]
	global_load_dwordx2 v[252:253], v[232:233], off
	global_load_dwordx2 v[254:255], v[232:233], off offset:32
	global_load_dwordx2 v[230:231], v[232:233], off offset:256
	s_nop 0
	global_load_dwordx2 v[232:233], v[232:233], off offset:288

;     __device__ __forceinline__ void operator()(const f32x4 (&acc)[2][2][4][2], const Unit& u, int wr, int wc, int fr, int fq) const {
;         const int row0 = u.pm * BM + wr * 64 + fr, col0 = u.pn * BM + wc * 32 + 4 * fq;
;         float r2[8];
;         int rown = row0; asm volatile("" : "+v"(rown));
; #pragma unroll
;         for (int g = 0; g < 8; ++g) { if constexpr (HAS_RS2) r2[g] = __hip_atomic_load(rs2 + row0 + (g >> 2) * HALF + (g & 3) * 16, __ATOMIC_RELAXED, __HIP_MEMORY_SCOPE_AGENT); else if constexpr (HAS_NRM) r2[g] = ssq[NRM_OFF + rown + (g >> 2) * HALF + (g & 3) * 16]; else r2[g] = 0.f; }
;         u32x2 raw[8][2][2];
;         if constexpr (BASEB) {
; #pragma unroll
;             for (int g = 0; g < 4; ++g)
; #pragma unroll
;                 for (int bj = 0; bj < 2; ++bj)
; #pragma unroll
;                     for (int n = 0; n < 2; ++n) raw[g][bj][n] = *(const u32x2*)((const bf16_t*)base + (size_t)(row0 + (g >> 2) * HALF + (g & 3) * 16) * 2048 + col0 + bj * HALF + n * 16);
;         }
;         f32x4 nx[2][2], ny[2][2]; if constexpr (!BASEB) { ldbase(nx, (size_t)row0 * 2048 + col0); ldbase(ny, (size_t)(row0 + 16) * 2048 + col0); }
; #pragma unroll
;         for (int g = 0; g < 8; ++g) { if constexpr (HAS_RS2) r2[g] = __builtin_amdgcn_rcpf(r2[g] * (1.0f / 2048.0f) + 1e-5f); else if constexpr (HAS_NRM) r2[g] = __builtin_amdgcn_sqrtf(r2[g] * (1.0f / 2048.0f) + 1e-5f);     else r2[g] = 1.f; }
; #pragma unroll
;         for (int g = 0; g < 8; ++g) {
;             const int ai = g >> 2, m = g & 3;
;             const int row = row0 + ai * HALF + m * 16; const size_t off = (size_t)row * 2048 + col0; float s = 0.f;
;             f32x4 bs[2][2];
;             if constexpr (BASEB) {
;                 if (g < 4) {
; #pragma unroll
;                     for (int bj = 0; bj < 2; ++bj)
; #pragma unroll
;                         for (int n = 0; n < 2; ++n) raw[g + 4][bj][n] = *(const u32x2*)((const bf16_t*)base + (size_t)(row0 + ((g + 4) >> 2) * HALF + ((g + 4) & 3) * 16) * 2048 + col0 + bj * HALF + n * 16);
;                 }
; #pragma unroll
;                 for (int bj = 0; bj < 2; ++bj)
; #pragma unroll
;                     for (int n = 0; n < 2; ++n) bs[bj][n] = bf4_to_f32(raw[g][bj][n]);
;             } else {
; #pragma unroll
;             for (int bj = 0; bj < 2; ++bj)
; #pragma unroll
.LBB0_654:
	v_mov_b64_e32 v[212:213], v[216:217]
	v_lshl_add_u32 v182, s24, 8, v1
	v_lshl_or_b32 v140, s22, 8, v196
	v_mov_b32_e32 v142, v182
	v_ashrrev_i32_e32 v141, 31, v140
	v_lshlrev_b64 v[156:157], 1, v[140:141]
	v_ashrrev_i32_e32 v183, 31, v182
	v_ashrrev_i32_e32 v143, 31, v142
	v_lshl_add_u64 v[148:149], s[90:91], 0, v[156:157]
	v_lshlrev_b64 v[210:211], 12, v[182:183]
	v_lshl_add_u64 v[142:143], v[142:143], 2, s[6:7]
	v_lshl_add_u64 v[144:145], v[148:149], 0, v[210:211]
	v_add_co_u32_e32 v216, vcc, 0x20000, v142
	v_addc_co_u32_e32 v217, vcc, 0, v143, vcc
	v_mov_b32_e32 v209, v131
	v_or_b32_e32 v172, 16, v182
	v_or_b32_e32 v160, 32, v182
	v_or_b32_e32 v146, 48, v182
	v_add_u32_e32 v142, 0x80, v182
	v_ashrrev_i32_e32 v173, 31, v172
	v_ashrrev_i32_e32 v161, 31, v160
	v_ashrrev_i32_e32 v147, 31, v146
	v_ashrrev_i32_e32 v143, 31, v142
	v_lshlrev_b64 v[184:185], 12, v[172:173]
	v_lshlrev_b64 v[170:171], 12, v[160:161]
	v_lshlrev_b64 v[158:159], 12, v[146:147]
	v_lshlrev_b64 v[144:145], 12, v[142:143]
	v_lshl_add_u64 v[150:151], v[148:149], 0, v[184:185]
	v_lshl_add_u64 v[152:153], v[148:149], 0, v[170:171]
	v_lshl_add_u64 v[148:149], v[148:149], 0, v[158:159]
	v_lshl_add_u64 v[154:155], s[90:91], 0, v[144:145]
	v_mov_b64_e32 v[192:193], v[234:235]
	v_mov_b64_e32 v[190:191], v[236:237]
	v_mov_b64_e32 v[188:189], v[238:239]
	v_mov_b64_e32 v[186:187], v[240:241]
	v_mov_b64_e32 v[180:181], v[244:245]
	v_mov_b64_e32 v[178:179], v[246:247]
	v_mov_b64_e32 v[176:177], v[248:249]
	v_mov_b64_e32 v[174:175], v[250:251]
	v_mov_b64_e32 v[168:169], v[252:253]
	v_mov_b64_e32 v[166:167], v[254:255]
	v_mov_b64_e32 v[164:165], v[230:231]
	v_mov_b64_e32 v[162:163], v[232:233]
	v_lshl_add_u64 v[148:149], v[154:155], 0, v[156:157]
	v_mov_b64_e32 v[154:155], v[222:223]
	v_mov_b64_e32 v[152:153], v[224:225]
	v_mov_b64_e32 v[150:151], v[226:227]
	s_nop 0
	v_mov_b64_e32 v[148:149], v[228:229]
	s_nop 0
	v_mov_b32_e32 v208, v133
	v_mov_b32_e32 v207, v135
	v_mov_b32_e32 v206, v137
	v_mov_b32_e32 v205, v243
	global_load_dword v204, v[216:217], off offset:576
	global_load_dword v203, v[216:217], off offset:640
	global_load_dword v202, v[216:217], off offset:704
	v_lshl_add_u64 v[210:211], s[70:71], 0, v[210:211]
	v_lshl_add_u64 v[210:211], v[210:211], 0, v[156:157]
	s_waitcnt vmcnt(3)
	v_lshlrev_b32_e32 v216, 16, v212
	v_and_b32_e32 v217, 0xffff0000, v212
	v_lshlrev_b32_e32 v212, 16, v213
	v_and_b32_e32 v213, 0xffff0000, v213
	v_lshlrev_b32_e32 v222, 16, v214
	v_fmamk_f32 v209, v209, 0x3a000000, v200
	v_sqrt_f32_e32 v228, v209
	v_and_b32_e32 v223, 0xffff0000, v214
	v_lshlrev_b32_e32 v214, 16, v215
	v_and_b32_e32 v215, 0xffff0000, v215
	v_pk_fma_f32 v[128:129], v[228:229], v[212:213], v[128:129] op_sel_hi:[0,1,1]
	v_pk_fma_f32 v[126:127], v[228:229], v[216:217], v[126:127] op_sel_hi:[0,1,1]
	v_pk_fma_f32 v[124:125], v[228:229], v[214:215], v[124:125] op_sel_hi:[0,1,1]
	v_pk_fma_f32 v[122:123], v[228:229], v[222:223], v[122:123] op_sel_hi:[0,1,1]
	v_mul_f32_e32 v214, v129, v129
	v_mul_f32_e32 v209, v127, v127
	v_cvt_pk_bf16_f32 v212, v126, v127
	v_cvt_pk_bf16_f32 v213, v128, v129
	v_mul_f32_e32 v127, v123, v123
	v_fmac_f32_e32 v214, v128, v128
	v_mul_f32_e32 v128, v125, v125
	v_lshlrev_b32_e32 v224, 16, v218
	v_and_b32_e32 v225, 0xffff0000, v218
	v_lshlrev_b32_e32 v218, 16, v219
	v_and_b32_e32 v219, 0xffff0000, v219
	v_fmac_f32_e32 v209, v126, v126
	v_fmac_f32_e32 v127, v122, v122
	v_fmac_f32_e32 v128, v124, v124
	v_lshlrev_b32_e32 v226, 16, v220
	v_and_b32_e32 v227, 0xffff0000, v220
	v_lshlrev_b32_e32 v220, 16, v221
	v_and_b32_e32 v221, 0xffff0000, v221
	v_add_f32_e32 v126, v209, v214
	v_add_f32_e32 v127, v127, v128
	v_pk_fma_f32 v[120:121], v[228:229], v[218:219], v[120:121] op_sel_hi:[0,1,1]
	v_pk_fma_f32 v[118:119], v[228:229], v[224:225], v[118:119] op_sel_hi:[0,1,1]
	global_store_dwordx2 v[210:211], v[212:213], off
	v_add_f32_e32 v126, v126, v127
	v_cvt_pk_bf16_f32 v122, v122, v123
	v_mul_f32_e32 v123, v119, v119
	v_mul_f32_e32 v127, v121, v121
	v_pk_fma_f32 v[116:117], v[228:229], v[220:221], v[116:117] op_sel_hi:[0,1,1]
	v_pk_fma_f32 v[128:129], v[228:229], v[226:227], v[114:115] op_sel_hi:[0,1,1]
	v_fmac_f32_e32 v123, v118, v118
	v_fmac_f32_e32 v127, v120, v120
	v_mul_f32_e32 v114, v129, v129
	v_mul_f32_e32 v115, v117, v117
	v_add_f32_e32 v123, v123, v127
	v_fmac_f32_e32 v114, v128, v128
	v_fmac_f32_e32 v115, v116, v116
	v_add_f32_e32 v123, v126, v123
	v_add_f32_e32 v114, v114, v115
	v_add_f32_e32 v114, v123, v114
	v_and_b32_e32 v123, 64, v201
	v_xor_b32_e32 v115, 16, v201
	v_add_u32_e32 v127, 64, v123
	v_cmp_lt_i32_e32 vcc, v115, v127
	v_cvt_pk_bf16_f32 v123, v124, v125
	global_store_dwordx2 v[210:211], v[122:123], off offset:32
	v_cvt_pk_bf16_f32 v118, v118, v119
	v_cvt_pk_bf16_f32 v119, v120, v121
	global_store_dwordx2 v[210:211], v[118:119], off offset:256
	v_cndmask_b32_e32 v115, v201, v115, vcc
	v_lshlrev_b32_e32 v126, 2, v115
	v_mov_b32_e32 v115, v114
	s_nop 1
	v_permlane16_swap_b32_e32 v115, v114
	v_cvt_pk_bf16_f32 v118, v128, v129
	v_cvt_pk_bf16_f32 v119, v116, v117
	global_store_dwordx2 v[210:211], v[118:119], off offset:288
	s_waitcnt lgkmcnt(0)
	v_add_f32_e32 v114, v114, v115
	v_xor_b32_e32 v115, 32, v201
	v_cmp_lt_i32_e32 vcc, v115, v127
	s_nop 1
	v_cndmask_b32_e32 v115, v201, v115, vcc
	v_lshlrev_b32_e32 v127, 2, v115
	v_mov_b32_e32 v115, v114
	s_nop 1
	v_permlane32_swap_b32_e32 v115, v114
	s_and_saveexec_b64 s[22:23], s[4:5]
	s_cbranch_execz .LBB0_656
	v_lshl_add_u64 v[116:117], v[182:183], 2, s[6:7]
	s_waitcnt lgkmcnt(0)
	v_add_f32_e32 v114, v114, v115
	global_atomic_add_f32 v[116:117], v114, off

; __device__ __forceinline__ unsigned cvt_pk_bf16(float lo, float hi) { unsigned r; asm volatile("v_cvt_pk_bf16_f32 %0, %1, %2" : "=v"(r) : "v"(lo), "v"(hi)); return r; }
; __device__ __forceinline__ f32x4 bf4_to_f32(u32x2 w) { f32x4 r; r[0] = __uint_as_float(w.x << 16); r[1] = __uint_as_float(w.x & 0xffff0000u); r[2] = __uint_as_float(w.y << 16); r[3] = __uint_as_float(w.y & 0xffff0000u); return r; }
;     __device__ __forceinline__ void operator()(const f32x4 (&acc)[2][2][4][2], const Unit& u, int wr, int wc, int fr, int fq) const {
;     ...
;         for (int g = 0; g < 8; ++g) {
;             const int ai = g >> 2, m = g & 3;
;             const int row = row0 + ai * HALF + m * 16; const size_t off = (size_t)row * 2048 + col0; float s = 0.f;
;             f32x4 bs[2][2];
;             if constexpr (BASEB) {
;                 if (g < 4) {
; #pragma unroll
;                     for (int bj = 0; bj < 2; ++bj)
; #pragma unroll
;                         for (int n = 0; n < 2; ++n) raw[g + 4][bj][n] = *(const u32x2*)((const bf16_t*)base + (size_t)(row0 + ((g + 4) >> 2) * HALF + ((g + 4) & 3) * 16) * 2048 + col0 + bj * HALF + n * 16);
;                 }
; #pragma unroll
;                 for (int bj = 0; bj < 2; ++bj)
; #pragma unroll
;                     for (int n = 0; n < 2; ++n) bs[bj][n] = bf4_to_f32(raw[g][bj][n]);
;             } else {
; #pragma unroll
;             for (int bj = 0; bj < 2; ++bj)
; #pragma unroll
;                 for (int n = 0; n < 2; ++n) { bs[bj][n] = nx[bj][n]; nx[bj][n] = ny[bj][n]; }
;             if (g < 6) ldbase(ny, (size_t)(row0 + ((g + 2) >> 2) * HALF + ((g + 2) & 3) * 16) * 2048 + col0);
;             }
; #pragma unroll
;             for (int bj = 0; bj < 2; ++bj)
; #pragma unroll
;                 for (int n = 0; n < 2; ++n) {
;                     const f32x4 o = HAS_NRM ? (bs[bj][n] * r2[g] + acc[ai][bj][m][n]) : (bs[bj][n] + acc[ai][bj][m][n] * r2[g]);
;                     if (HAS_OUT) *(f32x4*)(out + off + bj * HALF + n * 16) = o;
;                     s += (o[0] * o[0] + o[1] * o[1]) + (o[2] * o[2] + o[3] * o[3]);
;                     if (HAS_OUTB) { u32x2 w; w.x = cvt_pk_bf16(o[0], o[1]); w.y = cvt_pk_bf16(o[2], o[3]); *(u32x2*)(outb + off + bj * HALF + n * 16) = w; }
;                 }
;             s += __shfl_xor(s, 16); s += __shfl_xor(s, 32);
;             if (fq == 0) unsafeAtomicAdd(ssq + row, s);
.LBB0_664:
	s_or_b64 exec, exec, s[22:23]
	s_waitcnt vmcnt(27)
	v_fmamk_f32 v50, v204, 0x3a000000, v200
	v_sqrt_f32_e32 v50, v50
	v_lshlrev_b32_e32 v52, 16, v124
	v_and_b32_e32 v53, 0xffff0000, v124
	v_lshlrev_b32_e32 v54, 16, v125
	v_and_b32_e32 v55, 0xffff0000, v125
	s_waitcnt lgkmcnt(0)
	v_pk_fma_f32 v[48:49], v[50:51], v[54:55], v[48:49] op_sel_hi:[0,1,1]
	v_pk_fma_f32 v[46:47], v[50:51], v[52:53], v[46:47] op_sel_hi:[0,1,1]
	v_mul_f32_e32 v51, v47, v47
	v_mul_f32_e32 v52, v49, v49
	v_fmac_f32_e32 v51, v46, v46
	v_fmac_f32_e32 v52, v48, v48
	s_waitcnt vmcnt(26)
	v_lshlrev_b32_e32 v56, 16, v122
	v_and_b32_e32 v57, 0xffff0000, v122
	v_lshlrev_b32_e32 v58, 16, v123
	v_and_b32_e32 v59, 0xffff0000, v123
	v_add_f32_e32 v51, v51, v52
	v_cvt_pk_bf16_f32 v46, v46, v47
	v_cvt_pk_bf16_f32 v47, v48, v49
	v_lshl_add_u64 v[48:49], s[70:71], 0, v[116:117]
	v_lshl_add_u64 v[48:49], v[140:141], 1, v[48:49]
	v_pk_fma_f32 v[44:45], v[50:51], v[58:59], v[44:45] op_sel_hi:[0,1,1]
	v_pk_fma_f32 v[42:43], v[50:51], v[56:57], v[42:43] op_sel_hi:[0,1,1]
	s_waitcnt vmcnt(25)
	v_lshlrev_b32_e32 v60, 16, v120
	v_and_b32_e32 v61, 0xffff0000, v120
	v_lshlrev_b32_e32 v62, 16, v121
	v_and_b32_e32 v63, 0xffff0000, v121
	global_store_dwordx2 v[48:49], v[46:47], off
	v_mul_f32_e32 v46, v43, v43
	v_mul_f32_e32 v47, v45, v45
	v_fmac_f32_e32 v46, v42, v42
	v_fmac_f32_e32 v47, v44, v44
	v_pk_fma_f32 v[40:41], v[50:51], v[62:63], v[40:41] op_sel_hi:[0,1,1]
	v_pk_fma_f32 v[38:39], v[50:51], v[60:61], v[38:39] op_sel_hi:[0,1,1]
	v_add_f32_e32 v46, v46, v47
	v_cvt_pk_bf16_f32 v42, v42, v43
	v_mul_f32_e32 v43, v39, v39
	v_mul_f32_e32 v47, v41, v41
	v_fmac_f32_e32 v43, v38, v38
	v_fmac_f32_e32 v47, v40, v40
	s_waitcnt vmcnt(25)
	v_lshlrev_b32_e32 v64, 16, v118
	v_and_b32_e32 v65, 0xffff0000, v118
	v_lshlrev_b32_e32 v66, 16, v119
	v_and_b32_e32 v67, 0xffff0000, v119
	v_add_f32_e32 v46, v51, v46
	v_add_f32_e32 v43, v43, v47
	v_add_f32_e32 v43, v46, v43
	v_pk_fma_f32 v[36:37], v[50:51], v[66:67], v[36:37] op_sel_hi:[0,1,1]
	v_pk_fma_f32 v[46:47], v[50:51], v[64:65], v[34:35] op_sel_hi:[0,1,1]
	v_mul_f32_e32 v34, v47, v47
	v_mul_f32_e32 v35, v37, v37
	v_fmac_f32_e32 v34, v46, v46
	v_fmac_f32_e32 v35, v36, v36
	v_add_f32_e32 v34, v34, v35
	v_add_f32_e32 v34, v43, v34
	v_mov_b32_e32 v35, v34
	s_nop 1
	v_permlane16_swap_b32_e32 v35, v34
	v_cvt_pk_bf16_f32 v43, v44, v45
	global_store_dwordx2 v[48:49], v[42:43], off offset:32
	v_cvt_pk_bf16_f32 v38, v38, v39
	v_cvt_pk_bf16_f32 v39, v40, v41
	s_waitcnt lgkmcnt(0)
	v_add_f32_e32 v34, v34, v35
	v_mov_b32_e32 v35, v34
	s_nop 1
	v_permlane32_swap_b32_e32 v35, v34
	global_store_dwordx2 v[48:49], v[38:39], off offset:256
	v_cvt_pk_bf16_f32 v38, v46, v47
	v_cvt_pk_bf16_f32 v39, v36, v37
	global_store_dwordx2 v[48:49], v[38:39], off offset:288
	s_and_saveexec_b64 s[22:23], s[4:5]
	s_cbranch_execz .LBB0_666
	v_lshl_add_u64 v[36:37], v[114:115], 2, s[6:7]
	s_waitcnt lgkmcnt(0)
	v_add_f32_e32 v34, v34, v35
	global_atomic_add_f32 v[36:37], v34, off
